# flash loops: row-max seed max(max(x1,x1),max(x0,x0)) -> max(x0,x1), two VALU fewer per 32-key block (A, C, D loops)
# baseline (speedup 1.0000x reference)
; #define LAS __attribute__((address_space(3)))
; #define MFMA32(a, b, c) __builtin_amdgcn_mfma_f32_32x32x16_bf16((a), (b), (c), 0, 0, 0)
; template <int DQK, int NSUB, int MODE>
; __device__ __forceinline__ void flash_unit(LAS char* L, const bf16_t* Qp, int qpitch, const bf16_t* Kp, int kpitch, const bf16_t* Vp, int vpitch,
;                                            bf16_t* Op, int opitch, float lam, float oscale, const float* subln) {
;     ...
;         const char* Kb = Lg + buf * KBUF; LAS const char* Vb = L + OFF_V + buf * VBUF + voff;
; #pragma unroll
;         for (int s = 0; s < NSUB; ++s) {
;             f32x16 p0, p1;
; #pragma unroll
;             for (int d0 = 0; d0 < ND0; ++d0) { const bf16x8 k0 = *(const bf16x8*)(Kb + r32 * KPB + (s * DQK + 16 * d0 + 8 * hi) * 2); const bf16x8 k1 = *(const bf16x8*)(Kb + (32 + r32) * KPB + (s * DQK + 16 * d0 + 8 * hi) * 2);
;                 if (d0 == 0) { p0 = MFMA32(k0, qf[s][d0], negm[s]); p1 = MFMA32(k1, qf[s][d0], negm[s]); }
;                 else { p0 = MFMA32(k0, qf[s][d0], p0); p1 = MFMA32(k1, qf[s][d0], p1); } }
; #pragma unroll
;             for (int hf = 0; hf < 2; ++hf) {
;                 f32x16& ph = hf ? p1 : p0;
;                 float mx = fmaxf(ph[0], ph[1]);
; #pragma unroll
;                 for (int r = 2; r < 16; ++r) mx = fmaxf(mx, ph[r]);
;                 mx = fmaxf(mx, __shfl_xor(mx, 32));
;                 const bool first = (t == 0) && (hf == 0);
;                 if (first || __any(mx > 8.0f)) {
;                     const float dl = first ? mx : fmaxf(mx, 0.f); mref[s] += dl;
; #pragma unroll
;                     for (int r = 0; r < 16; ++r) { ph[r] -= dl; negm[s][r] = -mref[s]; }
;                     if (hf == 0) {
; #pragma unroll
;                         for (int r = 0; r < 16; ++r) p1[r] -= dl;
;                     }
;                     if (!first) { const float alpha = __builtin_amdgcn_exp2f(-dl); lrow[s] *= alpha;
; #pragma unroll
;                         for (int r = 0; r < 16; ++r) { o[s][0][r] *= alpha; o[s][1][r] *= alpha; } }
;                 }
.LBB0_579:
	s_and_b32 s8, s22, 1
	s_mul_i32 s9, s8, 0x2400
	v_add_u32_e32 v195, s9, v192
	v_add_u32_e32 v229, s9, v191
	ds_read_b128 v[96:99], v195
	ds_read_b128 v[100:103], v195 offset:32
	ds_read_b128 v[170:173], v195 offset:4608
	ds_read_b128 v[174:177], v195 offset:4640
	ds_read_b64_tr_b16 v[204:205], v229 offset:18432
	ds_read_b64_tr_b16 v[206:207], v229 offset:19584
	ds_read_b64_tr_b16 v[208:209], v229 offset:20736
	ds_read_b64_tr_b16 v[210:211], v229 offset:21888
	ds_read_b64_tr_b16 v[212:213], v229 offset:18496
	ds_read_b64_tr_b16 v[214:215], v229 offset:19648
	ds_read_b64_tr_b16 v[216:217], v229 offset:20800
	ds_read_b64_tr_b16 v[218:219], v229 offset:21952
	s_waitcnt lgkmcnt(8)
	v_mfma_f32_32x32x16_bf16 v[112:127], v[96:99], v[128:131], v[32:47]
	v_mfma_f32_32x32x16_bf16 v[112:127], v[100:103], v[132:135], v[112:127]
	s_nop 11
	v_mfma_f32_32x32x16_bf16 v[96:111], v[170:173], v[128:131], v[32:47]
	v_max_f32_e32 v158, v112, v113
	v_max3_f32 v158, v158, v114, v115
	v_max3_f32 v158, v158, v116, v117
	v_max3_f32 v158, v158, v118, v119
	v_max3_f32 v158, v158, v120, v121
	v_max3_f32 v158, v158, v122, v123
	v_max3_f32 v158, v158, v124, v125
	v_max3_f32 v158, v158, v126, v127
	v_mfma_f32_32x32x16_bf16 v[96:111], v[174:177], v[132:135], v[96:111]
	v_cmp_lt_f32_e32 vcc, s61, v158
	s_cbranch_vccz .LBB0_581
	ds_bpermute_b32 v169, v184, v158
	s_waitcnt lgkmcnt(0)
	v_max_f32_e32 v169, v169, v169
	v_max_f32_e32 v158, v158, v169
	v_max_f32_e32 v32, v158, v158
	v_max_f32_e32 v34, 0, v32
	v_exp_f32_e64 v36, -v34
	v_add_f32_e32 v159, v159, v34
	v_xor_b32_e32 v32, 0x80000000, v159
	v_pk_add_f32 v[112:113], v[112:113], v[34:35] op_sel_hi:[1,0] neg_lo:[0,1] neg_hi:[0,1]
	v_pk_add_f32 v[114:115], v[114:115], v[34:35] op_sel_hi:[1,0] neg_lo:[0,1] neg_hi:[0,1]
	v_pk_add_f32 v[116:117], v[116:117], v[34:35] op_sel_hi:[1,0] neg_lo:[0,1] neg_hi:[0,1]
	v_pk_add_f32 v[118:119], v[118:119], v[34:35] op_sel_hi:[1,0] neg_lo:[0,1] neg_hi:[0,1]
	v_pk_add_f32 v[120:121], v[120:121], v[34:35] op_sel_hi:[1,0] neg_lo:[0,1] neg_hi:[0,1]
	v_pk_add_f32 v[122:123], v[122:123], v[34:35] op_sel_hi:[1,0] neg_lo:[0,1] neg_hi:[0,1]
	v_pk_add_f32 v[124:125], v[124:125], v[34:35] op_sel_hi:[1,0] neg_lo:[0,1] neg_hi:[0,1]
	v_pk_add_f32 v[126:127], v[126:127], v[34:35] op_sel_hi:[1,0] neg_lo:[0,1] neg_hi:[0,1]
	v_sub_f32_e32 v111, v111, v34
	v_sub_f32_e32 v110, v110, v34
	v_sub_f32_e32 v109, v109, v34
	v_sub_f32_e32 v108, v108, v34
	v_sub_f32_e32 v107, v107, v34
	v_sub_f32_e32 v106, v106, v34
	v_sub_f32_e32 v105, v105, v34
	v_sub_f32_e32 v104, v104, v34
	v_sub_f32_e32 v103, v103, v34
	v_sub_f32_e32 v102, v102, v34
	v_sub_f32_e32 v101, v101, v34
	v_sub_f32_e32 v100, v100, v34
	v_sub_f32_e32 v99, v99, v34
	v_sub_f32_e32 v98, v98, v34
	v_sub_f32_e32 v97, v97, v34
	v_sub_f32_e32 v96, v96, v34
	v_pk_mul_f32 v[14:15], v[14:15], v[36:37] op_sel_hi:[1,0]
	v_pk_mul_f32 v[12:13], v[12:13], v[36:37] op_sel_hi:[1,0]
	v_pk_mul_f32 v[10:11], v[10:11], v[36:37] op_sel_hi:[1,0]
	v_pk_mul_f32 v[8:9], v[8:9], v[36:37] op_sel_hi:[1,0]
	v_pk_mul_f32 v[6:7], v[6:7], v[36:37] op_sel_hi:[1,0]
	v_pk_mul_f32 v[4:5], v[4:5], v[36:37] op_sel_hi:[1,0]
	v_pk_mul_f32 v[2:3], v[2:3], v[36:37] op_sel_hi:[1,0]
	v_pk_mul_f32 v[0:1], v[0:1], v[36:37] op_sel_hi:[1,0]
	v_pk_mul_f32 v[30:31], v[30:31], v[36:37] op_sel_hi:[1,0]
	v_pk_mul_f32 v[28:29], v[28:29], v[36:37] op_sel_hi:[1,0]
	v_pk_mul_f32 v[26:27], v[26:27], v[36:37] op_sel_hi:[1,0]
	v_pk_mul_f32 v[24:25], v[24:25], v[36:37] op_sel_hi:[1,0]
	v_pk_mul_f32 v[22:23], v[22:23], v[36:37] op_sel_hi:[1,0]
	v_pk_mul_f32 v[20:21], v[20:21], v[36:37] op_sel_hi:[1,0]
	v_pk_mul_f32 v[18:19], v[18:19], v[36:37] op_sel_hi:[1,0]
	v_pk_mul_f32 v[16:17], v[16:17], v[36:37] op_sel_hi:[1,0]
	v_mul_f32_e32 v168, v168, v36
	v_mov_b32_e32 v33, v32
	v_mov_b32_e32 v34, v32
	v_mov_b32_e32 v35, v32
	v_mov_b32_e32 v36, v32
	v_mov_b32_e32 v37, v32
	v_mov_b32_e32 v38, v32
	v_mov_b32_e32 v39, v32
	v_mov_b32_e32 v40, v32
	v_mov_b32_e32 v41, v32
	v_mov_b32_e32 v42, v32
	v_mov_b32_e32 v43, v32
	v_mov_b32_e32 v44, v32
	v_mov_b32_e32 v45, v32
	v_mov_b32_e32 v46, v32
	v_mov_b32_e32 v47, v32
; template <int DQK, int NSUB, int MODE>
; __device__ __forceinline__ void flash_unit(LAS char* L, const bf16_t* Qp, int qpitch, const bf16_t* Kp, int kpitch, const bf16_t* Vp, int vpitch,
;                                            bf16_t* Op, int opitch, float lam, float oscale, const float* subln) {
;     ...
;             for (int hf = 0; hf < 2; ++hf) {
;                 f32x16& ph = hf ? p1 : p0;
;                 float mx = fmaxf(ph[0], ph[1]);
; #pragma unroll
;                 for (int r = 2; r < 16; ++r) mx = fmaxf(mx, ph[r]);
;                 mx = fmaxf(mx, __shfl_xor(mx, 32));
;                 const bool first = (t == 0) && (hf == 0);
;                 if (first || __any(mx > 8.0f)) {
;                     const float dl = first ? mx : fmaxf(mx, 0.f); mref[s] += dl;
; #pragma unroll
;                     for (int r = 0; r < 16; ++r) { ph[r] -= dl; negm[s][r] = -mref[s]; }
;                     if (hf == 0) {
; #pragma unroll
;                         for (int r = 0; r < 16; ++r) p1[r] -= dl;
;                     }
;                     if (!first) { const float alpha = __builtin_amdgcn_exp2f(-dl); lrow[s] *= alpha;
; #pragma unroll
;                         for (int r = 0; r < 16; ++r) { o[s][0][r] *= alpha; o[s][1][r] *= alpha; } }
;                 }
; #pragma unroll
;                 for (int r = 0; r < 16; ++r) ph[r] = __builtin_amdgcn_exp2f(ph[r]);
;                 { typedef float f32x2_ __attribute__((ext_vector_type(2))); f32x2_ r2 = {ph[0], ph[1]};
; #pragma unroll
;                   for (int r = 2; r < 16; r += 2) r2 += (f32x2_){ph[r], ph[r + 1]};
;                   lrow[s] += r2[0] + r2[1]; }
;                 bf16x8 pf[2];
; #pragma unroll
;                 for (int k2 = 0; k2 < 2; ++k2) { u32x4 w;
; #pragma unroll
;                     for (int e = 0; e < 4; ++e) w[e] = cvt_pk_bf16(ph[8 * k2 + 2 * e], ph[8 * k2 + 2 * e + 1]);
;                     pf[k2] = __builtin_bit_cast(bf16x8, w); }
; #pragma unroll
;                 for (int db = 0; db < 2; ++db)
; #pragma unroll
;                     for (int k2 = 0; k2 < 2; ++k2) { const int ks = 2 * hf + k2; const v4i16_t lo = vtr(Vb + (16 * ks) * VPB + db * 64), hh = vtr(Vb + (16 * ks + 8) * VPB + db * 64);
;                         const bf16x8 vf = {lo[0], lo[1], lo[2], lo[3], hh[0], hh[1], hh[2], hh[3]};
;                         o[s][db] = MFMA32(vf, pf[k2], o[s][db]); }
.LBB0_581:
	v_exp_f32_e32 v112, v112
	v_exp_f32_e32 v113, v113
	v_exp_f32_e32 v114, v114
	v_exp_f32_e32 v115, v115
	v_exp_f32_e32 v116, v116
	v_exp_f32_e32 v117, v117
	v_exp_f32_e32 v118, v118
	v_exp_f32_e32 v119, v119
	v_exp_f32_e32 v120, v120
	v_exp_f32_e32 v121, v121
	v_exp_f32_e32 v122, v122
	v_exp_f32_e32 v123, v123
	v_pk_add_f32 v[170:171], v[112:113], v[114:115]
	v_add_u32_e32 v158, s9, v191
	v_pk_add_f32 v[170:171], v[116:117], v[170:171]
	v_cvt_pk_bf16_f32 v112, v112, v113
	v_pk_add_f32 v[170:171], v[118:119], v[170:171]
	v_cvt_pk_bf16_f32 v113, v114, v115
	v_pk_add_f32 v[170:171], v[120:121], v[170:171]
	v_cvt_pk_bf16_f32 v114, v116, v117
	v_pk_add_f32 v[170:171], v[122:123], v[170:171]
	v_cvt_pk_bf16_f32 v116, v120, v121
	v_cvt_pk_bf16_f32 v117, v122, v123
	ds_read_b64_tr_b16 v[220:221], v158 offset:23040
	ds_read_b64_tr_b16 v[222:223], v158 offset:24192
	v_cvt_pk_bf16_f32 v115, v118, v119
	v_exp_f32_e32 v124, v124
	v_exp_f32_e32 v125, v125
	s_waitcnt lgkmcnt(8)
	v_mfma_f32_32x32x16_bf16 v[0:15], v[204:207], v[112:115], v[0:15]
	v_exp_f32_e32 v126, v126
	v_exp_f32_e32 v127, v127
	ds_read_b64_tr_b16 v[224:225], v158 offset:25344
	ds_read_b64_tr_b16 v[226:227], v158 offset:26496
	v_cvt_pk_bf16_f32 v118, v124, v125
	v_pk_add_f32 v[170:171], v[124:125], v[170:171]
	v_cvt_pk_bf16_f32 v119, v126, v127
	v_pk_add_f32 v[170:171], v[126:127], v[170:171]
	s_waitcnt lgkmcnt(8)
	v_mfma_f32_32x32x16_bf16 v[0:15], v[208:211], v[116:119], v[0:15]
	ds_read_b64_tr_b16 v[236:237], v158 offset:23104
	ds_read_b64_tr_b16 v[238:239], v158 offset:24256
	v_add_f32_e32 v169, v170, v171
	v_add_f32_e32 v194, v168, v169
	s_waitcnt lgkmcnt(8)
	v_mfma_f32_32x32x16_bf16 v[16:31], v[212:215], v[112:115], v[16:31]
	s_waitcnt lgkmcnt(6)
	v_mfma_f32_32x32x16_bf16 v[16:31], v[216:219], v[116:119], v[16:31]
	v_max_f32_e32 v112, v96, v97
	v_max3_f32 v112, v112, v98, v99
	v_max3_f32 v112, v112, v100, v101
	v_max3_f32 v112, v112, v102, v103
	v_max3_f32 v112, v112, v104, v105
	v_max3_f32 v112, v112, v106, v107
	v_max3_f32 v112, v112, v108, v109
	v_max3_f32 v112, v112, v110, v111
	v_cmp_lt_f32_e32 vcc, s61, v112
	s_cbranch_vccz .LBB0_583
	ds_bpermute_b32 v113, v184, v112
	s_waitcnt lgkmcnt(0)
	v_max_f32_e32 v113, v113, v113
	v_max_f32_e32 v112, v112, v113
	v_max_f32_e32 v32, v112, v112
	v_max_f32_e32 v34, 0, v32
	v_exp_f32_e64 v36, -v34
	v_add_f32_e32 v159, v159, v34
	v_xor_b32_e32 v32, 0x80000000, v159
	v_pk_add_f32 v[96:97], v[96:97], v[34:35] op_sel_hi:[1,0] neg_lo:[0,1] neg_hi:[0,1]
	v_pk_add_f32 v[98:99], v[98:99], v[34:35] op_sel_hi:[1,0] neg_lo:[0,1] neg_hi:[0,1]
	v_pk_add_f32 v[100:101], v[100:101], v[34:35] op_sel_hi:[1,0] neg_lo:[0,1] neg_hi:[0,1]
	v_pk_add_f32 v[102:103], v[102:103], v[34:35] op_sel_hi:[1,0] neg_lo:[0,1] neg_hi:[0,1]
	v_pk_add_f32 v[104:105], v[104:105], v[34:35] op_sel_hi:[1,0] neg_lo:[0,1] neg_hi:[0,1]
	v_pk_add_f32 v[106:107], v[106:107], v[34:35] op_sel_hi:[1,0] neg_lo:[0,1] neg_hi:[0,1]
	v_pk_add_f32 v[108:109], v[108:109], v[34:35] op_sel_hi:[1,0] neg_lo:[0,1] neg_hi:[0,1]
	v_pk_add_f32 v[110:111], v[110:111], v[34:35] op_sel_hi:[1,0] neg_lo:[0,1] neg_hi:[0,1]
	v_pk_mul_f32 v[14:15], v[14:15], v[36:37] op_sel_hi:[1,0]
	v_pk_mul_f32 v[12:13], v[12:13], v[36:37] op_sel_hi:[1,0]
	v_pk_mul_f32 v[10:11], v[10:11], v[36:37] op_sel_hi:[1,0]
	v_pk_mul_f32 v[8:9], v[8:9], v[36:37] op_sel_hi:[1,0]
	v_pk_mul_f32 v[6:7], v[6:7], v[36:37] op_sel_hi:[1,0]
	v_pk_mul_f32 v[4:5], v[4:5], v[36:37] op_sel_hi:[1,0]
	v_pk_mul_f32 v[2:3], v[2:3], v[36:37] op_sel_hi:[1,0]
	v_pk_mul_f32 v[0:1], v[0:1], v[36:37] op_sel_hi:[1,0]
	v_pk_mul_f32 v[30:31], v[30:31], v[36:37] op_sel_hi:[1,0]
	v_pk_mul_f32 v[28:29], v[28:29], v[36:37] op_sel_hi:[1,0]
	v_pk_mul_f32 v[26:27], v[26:27], v[36:37] op_sel_hi:[1,0]
	v_pk_mul_f32 v[24:25], v[24:25], v[36:37] op_sel_hi:[1,0]
	v_pk_mul_f32 v[22:23], v[22:23], v[36:37] op_sel_hi:[1,0]
	v_pk_mul_f32 v[20:21], v[20:21], v[36:37] op_sel_hi:[1,0]
	v_pk_mul_f32 v[18:19], v[18:19], v[36:37] op_sel_hi:[1,0]
	v_pk_mul_f32 v[16:17], v[16:17], v[36:37] op_sel_hi:[1,0]
	v_mul_f32_e32 v194, v194, v36
	v_mov_b32_e32 v33, v32
	v_mov_b32_e32 v34, v32
	v_mov_b32_e32 v35, v32
	v_mov_b32_e32 v36, v32
	v_mov_b32_e32 v37, v32
	v_mov_b32_e32 v38, v32
	v_mov_b32_e32 v39, v32
	v_mov_b32_e32 v40, v32
	v_mov_b32_e32 v41, v32
	v_mov_b32_e32 v42, v32
	v_mov_b32_e32 v43, v32
	v_mov_b32_e32 v44, v32
	v_mov_b32_e32 v45, v32
	v_mov_b32_e32 v46, v32
	v_mov_b32_e32 v47, v32

; template <int DQK, int NSUB, int MODE>
; __device__ __forceinline__ void flash_unit(LAS char* L, const bf16_t* Qp, int qpitch, const bf16_t* Kp, int kpitch, const bf16_t* Vp, int vpitch,
;                                            bf16_t* Op, int opitch, float lam, float oscale, const float* subln) {
;     ...
;             for (int hf = 0; hf < 2; ++hf) {
;                 f32x16& ph = hf ? p1 : p0;
;                 float mx = fmaxf(ph[0], ph[1]);
; #pragma unroll
;                 for (int r = 2; r < 16; ++r) mx = fmaxf(mx, ph[r]);
;                 mx = fmaxf(mx, __shfl_xor(mx, 32));
;                 const bool first = (t == 0) && (hf == 0);
;                 if (first || __any(mx > 8.0f)) {
;                     const float dl = first ? mx : fmaxf(mx, 0.f); mref[s] += dl;
; #pragma unroll
;                     for (int r = 0; r < 16; ++r) { ph[r] -= dl; negm[s][r] = -mref[s]; }
;                     if (hf == 0) {
; #pragma unroll
;                         for (int r = 0; r < 16; ++r) p1[r] -= dl;
;                     }
;                     if (!first) { const float alpha = __builtin_amdgcn_exp2f(-dl); lrow[s] *= alpha;
; #pragma unroll
;                         for (int r = 0; r < 16; ++r) { o[s][0][r] *= alpha; o[s][1][r] *= alpha; } }
;                 }
; #pragma unroll
;                 for (int r = 0; r < 16; ++r) ph[r] = __builtin_amdgcn_exp2f(ph[r]);
;                 { typedef float f32x2_ __attribute__((ext_vector_type(2))); f32x2_ r2 = {ph[0], ph[1]};
; #pragma unroll
;                   for (int r = 2; r < 16; r += 2) r2 += (f32x2_){ph[r], ph[r + 1]};
;                   lrow[s] += r2[0] + r2[1]; }
;                 bf16x8 pf[2];
; #pragma unroll
;                 for (int k2 = 0; k2 < 2; ++k2) { u32x4 w;
; #pragma unroll
;                     for (int e = 0; e < 4; ++e) w[e] = cvt_pk_bf16(ph[8 * k2 + 2 * e], ph[8 * k2 + 2 * e + 1]);
;                     pf[k2] = __builtin_bit_cast(bf16x8, w); }
; #pragma unroll
;                 for (int db = 0; db < 2; ++db)
; #pragma unroll
;                     for (int k2 = 0; k2 < 2; ++k2) { const int ks = 2 * hf + k2; const v4i16_t lo = vtr(Vb + (16 * ks) * VPB + db * 64), hh = vtr(Vb + (16 * ks + 8) * VPB + db * 64);
;                         const bf16x8 vf = {lo[0], lo[1], lo[2], lo[3], hh[0], hh[1], hh[2], hh[3]};
;                         o[s][db] = MFMA32(vf, pf[k2], o[s][db]); }
.LBB0_585:
	v_exp_f32_e32 v112, v112
	v_exp_f32_e32 v113, v113
	v_exp_f32_e32 v114, v114
	v_exp_f32_e32 v115, v115
	v_exp_f32_e32 v116, v116
	v_exp_f32_e32 v117, v117
	v_exp_f32_e32 v118, v118
	v_exp_f32_e32 v119, v119
	v_exp_f32_e32 v120, v120
	v_exp_f32_e32 v121, v121
	v_exp_f32_e32 v122, v122
	v_exp_f32_e32 v123, v123
	v_pk_add_f32 v[196:197], v[112:113], v[114:115]
	v_cvt_pk_bf16_f32 v112, v112, v113
	v_pk_add_f32 v[196:197], v[116:117], v[196:197]
	v_cvt_pk_bf16_f32 v113, v114, v115
	v_pk_add_f32 v[196:197], v[118:119], v[196:197]
	v_cvt_pk_bf16_f32 v114, v116, v117
	v_pk_add_f32 v[196:197], v[120:121], v[196:197]
	v_cvt_pk_bf16_f32 v116, v120, v121
	v_pk_add_f32 v[196:197], v[122:123], v[196:197]
	v_cvt_pk_bf16_f32 v117, v122, v123
	v_cvt_pk_bf16_f32 v115, v118, v119
	v_exp_f32_e32 v124, v124
	v_exp_f32_e32 v125, v125
	s_waitcnt lgkmcnt(0)
	v_mfma_f32_32x32x16_bf16 v[48:63], v[204:207], v[112:115], v[48:63]
	v_exp_f32_e32 v126, v126
	v_exp_f32_e32 v127, v127
	v_cvt_pk_bf16_f32 v118, v124, v125
	v_pk_add_f32 v[196:197], v[124:125], v[196:197]
	v_cvt_pk_bf16_f32 v119, v126, v127
	v_pk_add_f32 v[196:197], v[126:127], v[196:197]
	s_waitcnt lgkmcnt(0)
	v_mfma_f32_32x32x16_bf16 v[48:63], v[208:211], v[116:119], v[48:63]
	v_add_f32_e32 v195, v196, v197
	s_waitcnt lgkmcnt(0)
	v_mfma_f32_32x32x16_bf16 v[64:79], v[212:215], v[112:115], v[64:79]
	s_waitcnt lgkmcnt(0)
	v_mfma_f32_32x32x16_bf16 v[64:79], v[216:219], v[116:119], v[64:79]
	v_max_f32_e32 v113, v96, v97
	v_max3_f32 v113, v113, v98, v99
	v_max3_f32 v113, v113, v100, v101
	v_max3_f32 v113, v113, v102, v103
	v_max3_f32 v113, v113, v104, v105
	v_max3_f32 v113, v113, v106, v107
	v_max3_f32 v113, v113, v108, v109
	v_max3_f32 v113, v113, v110, v111
	v_add_f32_e32 v112, v160, v195
	v_cmp_lt_f32_e32 vcc, s61, v113
	s_cbranch_vccz .LBB0_587
	ds_bpermute_b32 v114, v184, v113
	s_waitcnt lgkmcnt(0)
	v_max_f32_e32 v114, v114, v114
	v_max_f32_e32 v113, v113, v114
	v_max_f32_e32 v80, v113, v113
	v_max_f32_e32 v82, 0, v80
	v_exp_f32_e64 v84, -v82
	v_add_f32_e32 v161, v161, v82
	v_xor_b32_e32 v80, 0x80000000, v161
	v_pk_add_f32 v[96:97], v[96:97], v[82:83] op_sel_hi:[1,0] neg_lo:[0,1] neg_hi:[0,1]
	v_pk_add_f32 v[98:99], v[98:99], v[82:83] op_sel_hi:[1,0] neg_lo:[0,1] neg_hi:[0,1]
	v_pk_add_f32 v[100:101], v[100:101], v[82:83] op_sel_hi:[1,0] neg_lo:[0,1] neg_hi:[0,1]
	v_pk_add_f32 v[102:103], v[102:103], v[82:83] op_sel_hi:[1,0] neg_lo:[0,1] neg_hi:[0,1]
	v_pk_add_f32 v[104:105], v[104:105], v[82:83] op_sel_hi:[1,0] neg_lo:[0,1] neg_hi:[0,1]
	v_pk_add_f32 v[106:107], v[106:107], v[82:83] op_sel_hi:[1,0] neg_lo:[0,1] neg_hi:[0,1]
	v_pk_add_f32 v[108:109], v[108:109], v[82:83] op_sel_hi:[1,0] neg_lo:[0,1] neg_hi:[0,1]
	v_pk_add_f32 v[110:111], v[110:111], v[82:83] op_sel_hi:[1,0] neg_lo:[0,1] neg_hi:[0,1]
	v_pk_mul_f32 v[62:63], v[62:63], v[84:85] op_sel_hi:[1,0]
	v_pk_mul_f32 v[60:61], v[60:61], v[84:85] op_sel_hi:[1,0]
	v_pk_mul_f32 v[58:59], v[58:59], v[84:85] op_sel_hi:[1,0]
	v_pk_mul_f32 v[56:57], v[56:57], v[84:85] op_sel_hi:[1,0]
	v_pk_mul_f32 v[54:55], v[54:55], v[84:85] op_sel_hi:[1,0]
	v_pk_mul_f32 v[52:53], v[52:53], v[84:85] op_sel_hi:[1,0]
	v_pk_mul_f32 v[50:51], v[50:51], v[84:85] op_sel_hi:[1,0]
	v_pk_mul_f32 v[48:49], v[48:49], v[84:85] op_sel_hi:[1,0]
	v_pk_mul_f32 v[78:79], v[78:79], v[84:85] op_sel_hi:[1,0]
	v_pk_mul_f32 v[76:77], v[76:77], v[84:85] op_sel_hi:[1,0]
	v_pk_mul_f32 v[74:75], v[74:75], v[84:85] op_sel_hi:[1,0]
	v_pk_mul_f32 v[72:73], v[72:73], v[84:85] op_sel_hi:[1,0]
	v_pk_mul_f32 v[70:71], v[70:71], v[84:85] op_sel_hi:[1,0]
	v_pk_mul_f32 v[68:69], v[68:69], v[84:85] op_sel_hi:[1,0]
	v_pk_mul_f32 v[66:67], v[66:67], v[84:85] op_sel_hi:[1,0]
	v_pk_mul_f32 v[64:65], v[64:65], v[84:85] op_sel_hi:[1,0]
	v_mul_f32_e32 v112, v112, v84
	v_mov_b32_e32 v81, v80
	v_mov_b32_e32 v82, v80
	v_mov_b32_e32 v83, v80
	v_mov_b32_e32 v84, v80
	v_mov_b32_e32 v85, v80
	v_mov_b32_e32 v86, v80
	v_mov_b32_e32 v87, v80
	v_mov_b32_e32 v88, v80
	v_mov_b32_e32 v89, v80
	v_mov_b32_e32 v90, v80
	v_mov_b32_e32 v91, v80
	v_mov_b32_e32 v92, v80
	v_mov_b32_e32 v93, v80
	v_mov_b32_e32 v94, v80
	v_mov_b32_e32 v95, v80

; #define LAS __attribute__((address_space(3)))
; #define MFMA32(a, b, c) __builtin_amdgcn_mfma_f32_32x32x16_bf16((a), (b), (c), 0, 0, 0)
; template <int DQK, int NSUB, int MODE>
; __device__ __forceinline__ void flash_unit(LAS char* L, const bf16_t* Qp, int qpitch, const bf16_t* Kp, int kpitch, const bf16_t* Vp, int vpitch,
;                                            bf16_t* Op, int opitch, float lam, float oscale, const float* subln) {
;     ...
;         const char* Kb = Lg + buf * KBUF; LAS const char* Vb = L + OFF_V + buf * VBUF + voff;
; #pragma unroll
;         for (int s = 0; s < NSUB; ++s) {
;             f32x16 p0, p1;
; #pragma unroll
;             for (int d0 = 0; d0 < ND0; ++d0) { const bf16x8 k0 = *(const bf16x8*)(Kb + r32 * KPB + (s * DQK + 16 * d0 + 8 * hi) * 2); const bf16x8 k1 = *(const bf16x8*)(Kb + (32 + r32) * KPB + (s * DQK + 16 * d0 + 8 * hi) * 2);
;                 if (d0 == 0) { p0 = MFMA32(k0, qf[s][d0], negm[s]); p1 = MFMA32(k1, qf[s][d0], negm[s]); }
;                 else { p0 = MFMA32(k0, qf[s][d0], p0); p1 = MFMA32(k1, qf[s][d0], p1); } }
; #pragma unroll
;             for (int hf = 0; hf < 2; ++hf) {
;                 f32x16& ph = hf ? p1 : p0;
;                 float mx = fmaxf(ph[0], ph[1]);
; #pragma unroll
;                 for (int r = 2; r < 16; ++r) mx = fmaxf(mx, ph[r]);
;                 mx = fmaxf(mx, __shfl_xor(mx, 32));
;                 const bool first = (t == 0) && (hf == 0);
;                 if (first || __any(mx > 8.0f)) {
;                     const float dl = first ? mx : fmaxf(mx, 0.f); mref[s] += dl;
; #pragma unroll
;                     for (int r = 0; r < 16; ++r) { ph[r] -= dl; negm[s][r] = -mref[s]; }
;                     if (hf == 0) {
; #pragma unroll
;                         for (int r = 0; r < 16; ++r) p1[r] -= dl;
;                     }
;                     if (!first) { const float alpha = __builtin_amdgcn_exp2f(-dl); lrow[s] *= alpha;
; #pragma unroll
;                         for (int r = 0; r < 16; ++r) { o[s][0][r] *= alpha; o[s][1][r] *= alpha; } }
;                 }
.Lfc_612:
	s_and_b32 s8, s21, 1
	s_mul_i32 s9, s8, 0x3400
	v_add_u32_e32 v228, s9, v131
	s_mul_i32 s9, s8, 0x2400
	v_add_u32_e32 v229, s9, v130
	ds_read_b128 v[132:135], v228
	ds_read_b128 v[136:139], v228 offset:32
	ds_read_b128 v[144:147], v228 offset:64
	ds_read_b128 v[148:151], v228 offset:96
	ds_read_b128 v[152:155], v228 offset:128
	ds_read_b128 v[164:167], v228 offset:160
	ds_read_b128 v[168:171], v228 offset:6656
	ds_read_b128 v[172:175], v228 offset:6688
	ds_read_b128 v[176:179], v228 offset:6720
	ds_read_b128 v[180:183], v228 offset:6752
	ds_read_b128 v[196:199], v228 offset:6784
	ds_read_b128 v[200:203], v228 offset:6816
	s_waitcnt lgkmcnt(6)
	v_mfma_f32_32x32x16_bf16 v[64:79], v[132:135], v[100:103], v[32:47]
	v_mfma_f32_32x32x16_bf16 v[64:79], v[136:139], v[80:83], v[64:79]
	v_mfma_f32_32x32x16_bf16 v[64:79], v[144:147], v[84:87], v[64:79]
	v_mfma_f32_32x32x16_bf16 v[64:79], v[148:151], v[88:91], v[64:79]
	v_mfma_f32_32x32x16_bf16 v[64:79], v[152:155], v[92:95], v[64:79]
	v_mfma_f32_32x32x16_bf16 v[64:79], v[164:167], v[96:99], v[64:79]
	s_waitcnt lgkmcnt(0)
	v_mfma_f32_32x32x16_bf16 v[48:63], v[168:171], v[100:103], v[32:47]
	v_mfma_f32_32x32x16_bf16 v[48:63], v[172:175], v[80:83], v[48:63]
	ds_read_b64_tr_b16 v[204:205], v229 offset:26624
	ds_read_b64_tr_b16 v[206:207], v229 offset:27776
	ds_read_b64_tr_b16 v[208:209], v229 offset:28928
	ds_read_b64_tr_b16 v[210:211], v229 offset:30080
	ds_read_b64_tr_b16 v[212:213], v229 offset:26688
	ds_read_b64_tr_b16 v[214:215], v229 offset:27840
	ds_read_b64_tr_b16 v[216:217], v229 offset:28992
	ds_read_b64_tr_b16 v[218:219], v229 offset:30144
	ds_read_b64_tr_b16 v[132:133], v229 offset:31232
	ds_read_b64_tr_b16 v[134:135], v229 offset:32384
	ds_read_b64_tr_b16 v[136:137], v229 offset:33536
	ds_read_b64_tr_b16 v[138:139], v229 offset:34688
	ds_read_b64_tr_b16 v[144:145], v229 offset:31296
	ds_read_b64_tr_b16 v[146:147], v229 offset:32448
	ds_read_b64_tr_b16 v[148:149], v229 offset:33600
	ds_read_b64_tr_b16 v[150:151], v229 offset:34752
	v_max_f32_e32 v222, v64, v65
	v_mfma_f32_32x32x16_bf16 v[48:63], v[176:179], v[84:87], v[48:63]
	v_max3_f32 v222, v222, v66, v67
	v_max3_f32 v222, v222, v68, v69
	v_mfma_f32_32x32x16_bf16 v[48:63], v[180:183], v[88:91], v[48:63]
	v_max3_f32 v222, v222, v70, v71
	v_max3_f32 v222, v222, v72, v73
	v_mfma_f32_32x32x16_bf16 v[48:63], v[196:199], v[92:95], v[48:63]
	v_max3_f32 v222, v222, v74, v75
	v_max3_f32 v222, v222, v76, v77
	v_max3_f32 v222, v222, v78, v79
	v_mfma_f32_32x32x16_bf16 v[48:63], v[200:203], v[96:99], v[48:63]
	v_cmp_lt_f32_e32 vcc, s61, v222
	s_cbranch_vccz .Lfc_614
	ds_bpermute_b32 v223, v184, v222
	s_waitcnt lgkmcnt(0)
	v_max_f32_e32 v223, v223, v223
	v_max_f32_e32 v222, v222, v223
	v_max_f32_e32 v32, v222, v222
	v_max_f32_e32 v33, 0, v32
	v_exp_f32_e64 v34, -v33
	v_add_f32_e32 v119, v119, v33
	v_xor_b32_e32 v32, 0x80000000, v119
	v_sub_f32_e32 v79, v79, v33
	v_sub_f32_e32 v78, v78, v33
	v_sub_f32_e32 v77, v77, v33
	v_sub_f32_e32 v76, v76, v33
	v_sub_f32_e32 v75, v75, v33
	v_sub_f32_e32 v74, v74, v33
	v_sub_f32_e32 v73, v73, v33
	v_sub_f32_e32 v72, v72, v33
	v_sub_f32_e32 v71, v71, v33
	v_sub_f32_e32 v70, v70, v33
	v_sub_f32_e32 v69, v69, v33
	v_sub_f32_e32 v68, v68, v33
	v_sub_f32_e32 v67, v67, v33
	v_sub_f32_e32 v66, v66, v33
	v_sub_f32_e32 v65, v65, v33
	v_sub_f32_e32 v64, v64, v33
	v_sub_f32_e32 v63, v63, v33
	v_sub_f32_e32 v62, v62, v33
	v_sub_f32_e32 v61, v61, v33
	v_sub_f32_e32 v60, v60, v33
	v_sub_f32_e32 v59, v59, v33
	v_sub_f32_e32 v58, v58, v33
	v_sub_f32_e32 v57, v57, v33
	v_sub_f32_e32 v56, v56, v33
	v_sub_f32_e32 v55, v55, v33
	v_sub_f32_e32 v54, v54, v33
	v_sub_f32_e32 v53, v53, v33
	v_sub_f32_e32 v52, v52, v33
	v_sub_f32_e32 v51, v51, v33
	v_sub_f32_e32 v50, v50, v33
	v_sub_f32_e32 v49, v49, v33
	v_sub_f32_e32 v48, v48, v33
	v_pk_mul_f32 v[30:31], v[30:31], v[34:35] op_sel_hi:[1,0]
	v_pk_mul_f32 v[28:29], v[28:29], v[34:35] op_sel_hi:[1,0]
	v_pk_mul_f32 v[26:27], v[26:27], v[34:35] op_sel_hi:[1,0]
	v_pk_mul_f32 v[24:25], v[24:25], v[34:35] op_sel_hi:[1,0]
	v_pk_mul_f32 v[22:23], v[22:23], v[34:35] op_sel_hi:[1,0]
	v_pk_mul_f32 v[20:21], v[20:21], v[34:35] op_sel_hi:[1,0]
	v_pk_mul_f32 v[18:19], v[18:19], v[34:35] op_sel_hi:[1,0]
	v_pk_mul_f32 v[16:17], v[16:17], v[34:35] op_sel_hi:[1,0]
	v_pk_mul_f32 v[14:15], v[14:15], v[34:35] op_sel_hi:[1,0]
	v_pk_mul_f32 v[12:13], v[12:13], v[34:35] op_sel_hi:[1,0]
	v_pk_mul_f32 v[10:11], v[10:11], v[34:35] op_sel_hi:[1,0]
	v_pk_mul_f32 v[8:9], v[8:9], v[34:35] op_sel_hi:[1,0]
	v_pk_mul_f32 v[6:7], v[6:7], v[34:35] op_sel_hi:[1,0]
	v_pk_mul_f32 v[4:5], v[4:5], v[34:35] op_sel_hi:[1,0]
	v_pk_mul_f32 v[2:3], v[2:3], v[34:35] op_sel_hi:[1,0]
	v_pk_mul_f32 v[0:1], v[0:1], v[34:35] op_sel_hi:[1,0]
	v_mul_f32_e32 v118, v118, v34
	v_mov_b32_e32 v33, v32
	v_mov_b32_e32 v34, v32
	v_mov_b32_e32 v35, v32
	v_mov_b32_e32 v36, v32
	v_mov_b32_e32 v37, v32
	v_mov_b32_e32 v38, v32
	v_mov_b32_e32 v39, v32
	v_mov_b32_e32 v40, v32
	v_mov_b32_e32 v41, v32
	v_mov_b32_e32 v42, v32
	v_mov_b32_e32 v43, v32
	v_mov_b32_e32 v44, v32
	v_mov_b32_e32 v45, v32
	v_mov_b32_e32 v46, v32
	v_mov_b32_e32 v47, v32
; template <int DQK, int NSUB, int MODE>
; __device__ __forceinline__ void flash_unit(LAS char* L, const bf16_t* Qp, int qpitch, const bf16_t* Kp, int kpitch, const bf16_t* Vp, int vpitch,
;                                            bf16_t* Op, int opitch, float lam, float oscale, const float* subln) {
;     ...
;             for (int hf = 0; hf < 2; ++hf) {
;                 f32x16& ph = hf ? p1 : p0;
;                 float mx = fmaxf(ph[0], ph[1]);
; #pragma unroll
;                 for (int r = 2; r < 16; ++r) mx = fmaxf(mx, ph[r]);
;                 mx = fmaxf(mx, __shfl_xor(mx, 32));
;                 const bool first = (t == 0) && (hf == 0);
;                 if (first || __any(mx > 8.0f)) {
;                     const float dl = first ? mx : fmaxf(mx, 0.f); mref[s] += dl;
; #pragma unroll
;                     for (int r = 0; r < 16; ++r) { ph[r] -= dl; negm[s][r] = -mref[s]; }
;                     if (hf == 0) {
; #pragma unroll
;                         for (int r = 0; r < 16; ++r) p1[r] -= dl;
;                     }
;                     if (!first) { const float alpha = __builtin_amdgcn_exp2f(-dl); lrow[s] *= alpha;
; #pragma unroll
;                         for (int r = 0; r < 16; ++r) { o[s][0][r] *= alpha; o[s][1][r] *= alpha; } }
;                 }
; #pragma unroll
;                 for (int r = 0; r < 16; ++r) ph[r] = __builtin_amdgcn_exp2f(ph[r]);
;                 { typedef float f32x2_ __attribute__((ext_vector_type(2))); f32x2_ r2 = {ph[0], ph[1]};
; #pragma unroll
;                   for (int r = 2; r < 16; r += 2) r2 += (f32x2_){ph[r], ph[r + 1]};
;                   lrow[s] += r2[0] + r2[1]; }
;                 bf16x8 pf[2];
; #pragma unroll
;                 for (int k2 = 0; k2 < 2; ++k2) { u32x4 w;
; #pragma unroll
;                     for (int e = 0; e < 4; ++e) w[e] = cvt_pk_bf16(ph[8 * k2 + 2 * e], ph[8 * k2 + 2 * e + 1]);
;                     pf[k2] = __builtin_bit_cast(bf16x8, w); }
; #pragma unroll
;                 for (int db = 0; db < 2; ++db)
; #pragma unroll
;                     for (int k2 = 0; k2 < 2; ++k2) { const int ks = 2 * hf + k2; const v4i16_t lo = vtr(Vb + (16 * ks) * VPB + db * 64), hh = vtr(Vb + (16 * ks + 8) * VPB + db * 64);
;                         const bf16x8 vf = {lo[0], lo[1], lo[2], lo[3], hh[0], hh[1], hh[2], hh[3]};
;                         o[s][db] = MFMA32(vf, pf[k2], o[s][db]); }
.Lfc_614:
	v_exp_f32_e32 v64, v64
	v_exp_f32_e32 v65, v65
	v_exp_f32_e32 v220, v66
	v_exp_f32_e32 v221, v67
	v_exp_f32_e32 v68, v68
	v_exp_f32_e32 v69, v69
	v_exp_f32_e32 v70, v70
	v_exp_f32_e32 v71, v71
	v_exp_f32_e32 v72, v72
	v_exp_f32_e32 v73, v73
	v_exp_f32_e32 v74, v74
	v_exp_f32_e32 v75, v75
	v_pk_add_f32 v[66:67], v[64:65], v[220:221]
	v_exp_f32_e32 v76, v76
	v_exp_f32_e32 v77, v77
	v_pk_add_f32 v[66:67], v[68:69], v[66:67]
	v_exp_f32_e32 v78, v78
	v_exp_f32_e32 v79, v79
	v_pk_add_f32 v[66:67], v[70:71], v[66:67]
	v_pk_add_f32 v[66:67], v[72:73], v[66:67]
	v_cvt_pk_bf16_f32 v68, v68, v69
	v_pk_add_f32 v[66:67], v[74:75], v[66:67]
	v_cvt_pk_bf16_f32 v69, v70, v71
	v_pk_add_f32 v[66:67], v[76:77], v[66:67]
	v_cvt_pk_bf16_f32 v70, v72, v73
	v_pk_add_f32 v[222:223], v[78:79], v[66:67]
	v_cvt_pk_bf16_f32 v66, v64, v65
	v_cvt_pk_bf16_f32 v71, v74, v75
	v_cvt_pk_bf16_f32 v72, v76, v77
	v_cvt_pk_bf16_f32 v67, v220, v221
	v_cvt_pk_bf16_f32 v73, v78, v79
	v_add_f32_e32 v65, v222, v223
	s_waitcnt lgkmcnt(0)
	v_mfma_f32_32x32x16_bf16 v[0:15], v[204:207], v[66:69], v[0:15]
	v_add_f32_e32 v65, v118, v65
	v_max_f32_e32 v224, v48, v49
	v_mfma_f32_32x32x16_bf16 v[0:15], v[208:211], v[70:73], v[0:15]
	v_max3_f32 v224, v224, v50, v51
	v_max3_f32 v224, v224, v52, v53
	v_max3_f32 v224, v224, v54, v55
	v_max3_f32 v224, v224, v56, v57
	v_mfma_f32_32x32x16_bf16 v[16:31], v[212:215], v[66:69], v[16:31]
	v_max3_f32 v224, v224, v58, v59
	v_max3_f32 v224, v224, v60, v61
	v_max3_f32 v224, v224, v62, v63
	v_mfma_f32_32x32x16_bf16 v[16:31], v[216:219], v[70:73], v[16:31]
	v_cmp_lt_f32_e32 vcc, s61, v224
	s_cbranch_vccz .Lfc_616
	ds_bpermute_b32 v225, v184, v224
	s_waitcnt lgkmcnt(0)
	v_max_f32_e32 v225, v225, v225
	v_max_f32_e32 v224, v224, v225
	v_max_f32_e32 v32, v224, v224
	v_max_f32_e32 v33, 0, v32
	v_exp_f32_e64 v34, -v33
	v_add_f32_e32 v119, v119, v33
	v_xor_b32_e32 v32, 0x80000000, v119
	v_sub_f32_e32 v63, v63, v33
	v_sub_f32_e32 v62, v62, v33
	v_sub_f32_e32 v61, v61, v33
	v_sub_f32_e32 v60, v60, v33
	v_sub_f32_e32 v59, v59, v33
	v_sub_f32_e32 v58, v58, v33
	v_sub_f32_e32 v57, v57, v33
	v_sub_f32_e32 v56, v56, v33
	v_sub_f32_e32 v55, v55, v33
	v_sub_f32_e32 v54, v54, v33
	v_sub_f32_e32 v53, v53, v33
	v_sub_f32_e32 v52, v52, v33
	v_sub_f32_e32 v51, v51, v33
	v_sub_f32_e32 v50, v50, v33
	v_sub_f32_e32 v49, v49, v33
	v_sub_f32_e32 v48, v48, v33
	v_pk_mul_f32 v[14:15], v[14:15], v[34:35] op_sel_hi:[1,0]
	v_pk_mul_f32 v[12:13], v[12:13], v[34:35] op_sel_hi:[1,0]
	v_pk_mul_f32 v[10:11], v[10:11], v[34:35] op_sel_hi:[1,0]
	v_pk_mul_f32 v[8:9], v[8:9], v[34:35] op_sel_hi:[1,0]
	v_pk_mul_f32 v[6:7], v[6:7], v[34:35] op_sel_hi:[1,0]
	v_pk_mul_f32 v[4:5], v[4:5], v[34:35] op_sel_hi:[1,0]
	v_pk_mul_f32 v[2:3], v[2:3], v[34:35] op_sel_hi:[1,0]
	v_pk_mul_f32 v[0:1], v[0:1], v[34:35] op_sel_hi:[1,0]
	v_pk_mul_f32 v[30:31], v[30:31], v[34:35] op_sel_hi:[1,0]
	v_pk_mul_f32 v[28:29], v[28:29], v[34:35] op_sel_hi:[1,0]
	v_pk_mul_f32 v[26:27], v[26:27], v[34:35] op_sel_hi:[1,0]
	v_pk_mul_f32 v[24:25], v[24:25], v[34:35] op_sel_hi:[1,0]
	v_pk_mul_f32 v[22:23], v[22:23], v[34:35] op_sel_hi:[1,0]
	v_pk_mul_f32 v[20:21], v[20:21], v[34:35] op_sel_hi:[1,0]
	v_pk_mul_f32 v[18:19], v[18:19], v[34:35] op_sel_hi:[1,0]
	v_pk_mul_f32 v[16:17], v[16:17], v[34:35] op_sel_hi:[1,0]
	v_mul_f32_e32 v65, v65, v34
	v_mov_b32_e32 v33, v32
	v_mov_b32_e32 v34, v32
	v_mov_b32_e32 v35, v32
	v_mov_b32_e32 v36, v32
	v_mov_b32_e32 v37, v32
	v_mov_b32_e32 v38, v32
	v_mov_b32_e32 v39, v32
	v_mov_b32_e32 v40, v32
	v_mov_b32_e32 v41, v32
	v_mov_b32_e32 v42, v32
	v_mov_b32_e32 v43, v32
	v_mov_b32_e32 v44, v32
	v_mov_b32_e32 v45, v32
	v_mov_b32_e32 v46, v32
	v_mov_b32_e32 v47, v32

; #define LAS __attribute__((address_space(3)))
; #define MFMA32(a, b, c) __builtin_amdgcn_mfma_f32_32x32x16_bf16((a), (b), (c), 0, 0, 0)
; template <int DQK, int NSUB, int MODE>
; __device__ __forceinline__ void flash_unit(LAS char* L, const bf16_t* Qp, int qpitch, const bf16_t* Kp, int kpitch, const bf16_t* Vp, int vpitch,
;                                            bf16_t* Op, int opitch, float lam, float oscale, const float* subln) {
;     ...
;         if (t + 1 < SEQ / 64) { const size_t ko = (size_t)(t + 1) * 64 * kpitch, vo = (size_t)(t + 1) * 64 * vpitch;
;             rk1 = *(const u32x4*)(kg1 + ko); if (has2) rk2 = *(const u32x4*)(kg2 + ko); rv1 = *(const u32x4*)(vg1 + vo); }
;         const char* Kb = Lg + buf * KBUF; LAS const char* Vb = L + OFF_V + buf * VBUF + voff;
; #pragma unroll
;         for (int s = 0; s < NSUB; ++s) {
;             f32x16 p0, p1;
; #pragma unroll
;             for (int d0 = 0; d0 < ND0; ++d0) { const bf16x8 k0 = *(const bf16x8*)(Kb + r32 * KPB + (s * DQK + 16 * d0 + 8 * hi) * 2); const bf16x8 k1 = *(const bf16x8*)(Kb + (32 + r32) * KPB + (s * DQK + 16 * d0 + 8 * hi) * 2);
;                 if (d0 == 0) { p0 = MFMA32(k0, qf[s][d0], negm[s]); p1 = MFMA32(k1, qf[s][d0], negm[s]); }
;                 else { p0 = MFMA32(k0, qf[s][d0], p0); p1 = MFMA32(k1, qf[s][d0], p1); } }
; #pragma unroll
;             for (int hf = 0; hf < 2; ++hf) {
;                 f32x16& ph = hf ? p1 : p0;
;                 float mx = fmaxf(ph[0], ph[1]);
; #pragma unroll
;                 for (int r = 2; r < 16; ++r) mx = fmaxf(mx, ph[r]);
;                 mx = fmaxf(mx, __shfl_xor(mx, 32));
;                 const bool first = (t == 0) && (hf == 0);
;                 if (first || __any(mx > 8.0f)) {
;                     const float dl = first ? mx : fmaxf(mx, 0.f); mref[s] += dl;
; #pragma unroll
;                     for (int r = 0; r < 16; ++r) { ph[r] -= dl; negm[s][r] = -mref[s]; }
;                     if (hf == 0) {
; #pragma unroll
;                         for (int r = 0; r < 16; ++r) p1[r] -= dl;
;                     }
;                     if (!first) { const float alpha = __builtin_amdgcn_exp2f(-dl); lrow[s] *= alpha;
; #pragma unroll
;                         for (int r = 0; r < 16; ++r) { o[s][0][r] *= alpha; o[s][1][r] *= alpha; } }
;                 }
.Lfd_638:
	s_or_b64 exec, exec, s[8:9]
	v_lshl_add_u64 v[222:223], v[128:129], 0, s[10:11]
	global_load_dwordx4 v[116:119], v[222:223], off
	s_and_b32 s8, s14, 1
	s_mul_i32 s9, s8, 0x2400
	v_add_u32_e32 v224, s9, v139
	v_add_u32_e32 v220, s9, v135
	ds_read_b128 v[32:35], v224
	ds_read_b128 v[36:39], v224 offset:32
	ds_read_b128 v[40:43], v224 offset:64
	ds_read_b128 v[44:47], v224 offset:96
	ds_read_b128 v[144:147], v224 offset:4608
	ds_read_b128 v[148:151], v224 offset:4640
	ds_read_b128 v[152:155], v224 offset:4672
	ds_read_b128 v[164:167], v224 offset:4704
	s_waitcnt lgkmcnt(4)
	v_mfma_f32_32x32x16_bf16 v[80:95], v[32:35], v[108:111], v[48:63]
	v_mfma_f32_32x32x16_bf16 v[80:95], v[36:39], v[104:107], v[80:95]
	v_mfma_f32_32x32x16_bf16 v[80:95], v[40:43], v[100:103], v[80:95]
	v_mfma_f32_32x32x16_bf16 v[80:95], v[44:47], v[96:99], v[80:95]
	s_waitcnt lgkmcnt(0)
	v_mfma_f32_32x32x16_bf16 v[64:79], v[144:147], v[108:111], v[48:63]
	v_mfma_f32_32x32x16_bf16 v[64:79], v[148:151], v[104:107], v[64:79]
	ds_read_b64_tr_b16 v[204:205], v220 offset:18432
	ds_read_b64_tr_b16 v[206:207], v220 offset:19584
	ds_read_b64_tr_b16 v[208:209], v220 offset:20736
	ds_read_b64_tr_b16 v[210:211], v220 offset:21888
	ds_read_b64_tr_b16 v[212:213], v220 offset:18496
	ds_read_b64_tr_b16 v[214:215], v220 offset:19648
	ds_read_b64_tr_b16 v[216:217], v220 offset:20800
	ds_read_b64_tr_b16 v[218:219], v220 offset:21952
	ds_read_b64_tr_b16 v[168:169], v220 offset:23040
	ds_read_b64_tr_b16 v[170:171], v220 offset:24192
	ds_read_b64_tr_b16 v[172:173], v220 offset:25344
	ds_read_b64_tr_b16 v[174:175], v220 offset:26496
	ds_read_b64_tr_b16 v[176:177], v220 offset:23104
	ds_read_b64_tr_b16 v[178:179], v220 offset:24256
	ds_read_b64_tr_b16 v[180:181], v220 offset:25408
	ds_read_b64_tr_b16 v[182:183], v220 offset:26560
	v_max_f32_e32 v222, v80, v81
	v_mfma_f32_32x32x16_bf16 v[64:79], v[152:155], v[100:103], v[64:79]
	v_max3_f32 v222, v222, v82, v83
	v_max3_f32 v222, v222, v84, v85
	v_max3_f32 v222, v222, v86, v87
	v_max3_f32 v222, v222, v88, v89
	v_mfma_f32_32x32x16_bf16 v[64:79], v[164:167], v[96:99], v[64:79]
	v_max3_f32 v222, v222, v90, v91
	v_max3_f32 v222, v222, v92, v93
	v_max3_f32 v222, v222, v94, v95
	v_cmp_lt_f32_e32 vcc, s61, v222
	s_cbranch_vccz .Lfd_641
	ds_bpermute_b32 v223, v184, v222
	s_waitcnt lgkmcnt(0)
	v_max_f32_e32 v223, v223, v223
	v_max_f32_e32 v222, v222, v223
	v_max_f32_e32 v222, v222, v222
	v_max_f32_e32 v223, 0, v222
	v_exp_f32_e64 v224, -v223
	v_add_f32_e32 v127, v127, v223
	v_xor_b32_e32 v222, 0x80000000, v127
	v_sub_f32_e32 v95, v95, v223
	v_sub_f32_e32 v94, v94, v223
	v_sub_f32_e32 v93, v93, v223
	v_sub_f32_e32 v92, v92, v223
	v_sub_f32_e32 v91, v91, v223
	v_sub_f32_e32 v90, v90, v223
	v_sub_f32_e32 v89, v89, v223
	v_sub_f32_e32 v88, v88, v223
	v_sub_f32_e32 v87, v87, v223
	v_sub_f32_e32 v86, v86, v223
	v_sub_f32_e32 v85, v85, v223
	v_sub_f32_e32 v84, v84, v223
	v_sub_f32_e32 v83, v83, v223
	v_sub_f32_e32 v82, v82, v223
	v_sub_f32_e32 v81, v81, v223
	v_sub_f32_e32 v80, v80, v223
	v_sub_f32_e32 v79, v79, v223
	v_sub_f32_e32 v78, v78, v223
	v_sub_f32_e32 v77, v77, v223
	v_sub_f32_e32 v76, v76, v223
	v_sub_f32_e32 v75, v75, v223
	v_sub_f32_e32 v74, v74, v223
	v_sub_f32_e32 v73, v73, v223
	v_sub_f32_e32 v72, v72, v223
	v_sub_f32_e32 v71, v71, v223
	v_sub_f32_e32 v70, v70, v223
	v_sub_f32_e32 v69, v69, v223
	v_sub_f32_e32 v68, v68, v223
	v_sub_f32_e32 v67, v67, v223
	v_sub_f32_e32 v66, v66, v223
	v_sub_f32_e32 v65, v65, v223
	v_sub_f32_e32 v64, v64, v223
	v_pk_mul_f32 v[30:31], v[30:31], v[224:225] op_sel_hi:[1,0]
	v_pk_mul_f32 v[28:29], v[28:29], v[224:225] op_sel_hi:[1,0]
	v_pk_mul_f32 v[26:27], v[26:27], v[224:225] op_sel_hi:[1,0]
	v_pk_mul_f32 v[24:25], v[24:25], v[224:225] op_sel_hi:[1,0]
	v_pk_mul_f32 v[22:23], v[22:23], v[224:225] op_sel_hi:[1,0]
	v_pk_mul_f32 v[20:21], v[20:21], v[224:225] op_sel_hi:[1,0]
	v_pk_mul_f32 v[18:19], v[18:19], v[224:225] op_sel_hi:[1,0]
	v_pk_mul_f32 v[16:17], v[16:17], v[224:225] op_sel_hi:[1,0]
	v_pk_mul_f32 v[14:15], v[14:15], v[224:225] op_sel_hi:[1,0]
	v_pk_mul_f32 v[12:13], v[12:13], v[224:225] op_sel_hi:[1,0]
	v_pk_mul_f32 v[10:11], v[10:11], v[224:225] op_sel_hi:[1,0]
	v_pk_mul_f32 v[8:9], v[8:9], v[224:225] op_sel_hi:[1,0]
	v_pk_mul_f32 v[6:7], v[6:7], v[224:225] op_sel_hi:[1,0]
	v_pk_mul_f32 v[4:5], v[4:5], v[224:225] op_sel_hi:[1,0]
	v_pk_mul_f32 v[2:3], v[2:3], v[224:225] op_sel_hi:[1,0]
	v_pk_mul_f32 v[0:1], v[0:1], v[224:225] op_sel_hi:[1,0]
	v_mul_f32_e32 v126, v126, v224
	v_mov_b32_e32 v48, v222
	v_mov_b32_e32 v49, v222
	v_mov_b32_e32 v50, v222
	v_mov_b32_e32 v51, v222
	v_mov_b32_e32 v52, v222
	v_mov_b32_e32 v53, v222
	v_mov_b32_e32 v54, v222
	v_mov_b32_e32 v55, v222
	v_mov_b32_e32 v56, v222
	v_mov_b32_e32 v57, v222
	v_mov_b32_e32 v58, v222
	v_mov_b32_e32 v59, v222
	v_mov_b32_e32 v60, v222
	v_mov_b32_e32 v61, v222
	v_mov_b32_e32 v62, v222
	v_mov_b32_e32 v63, v222
; template <int DQK, int NSUB, int MODE>
; __device__ __forceinline__ void flash_unit(LAS char* L, const bf16_t* Qp, int qpitch, const bf16_t* Kp, int kpitch, const bf16_t* Vp, int vpitch,
;                                            bf16_t* Op, int opitch, float lam, float oscale, const float* subln) {
;     ...
;             for (int hf = 0; hf < 2; ++hf) {
;                 f32x16& ph = hf ? p1 : p0;
;                 float mx = fmaxf(ph[0], ph[1]);
; #pragma unroll
;                 for (int r = 2; r < 16; ++r) mx = fmaxf(mx, ph[r]);
;                 mx = fmaxf(mx, __shfl_xor(mx, 32));
;                 const bool first = (t == 0) && (hf == 0);
;                 if (first || __any(mx > 8.0f)) {
;                     const float dl = first ? mx : fmaxf(mx, 0.f); mref[s] += dl;
; #pragma unroll
;                     for (int r = 0; r < 16; ++r) { ph[r] -= dl; negm[s][r] = -mref[s]; }
;                     if (hf == 0) {
; #pragma unroll
;                         for (int r = 0; r < 16; ++r) p1[r] -= dl;
;                     }
;                     if (!first) { const float alpha = __builtin_amdgcn_exp2f(-dl); lrow[s] *= alpha;
; #pragma unroll
;                         for (int r = 0; r < 16; ++r) { o[s][0][r] *= alpha; o[s][1][r] *= alpha; } }
;                 }
; #pragma unroll
;                 for (int r = 0; r < 16; ++r) ph[r] = __builtin_amdgcn_exp2f(ph[r]);
;                 { typedef float f32x2_ __attribute__((ext_vector_type(2))); f32x2_ r2 = {ph[0], ph[1]};
; #pragma unroll
;                   for (int r = 2; r < 16; r += 2) r2 += (f32x2_){ph[r], ph[r + 1]};
;                   lrow[s] += r2[0] + r2[1]; }
;                 bf16x8 pf[2];
; #pragma unroll
;                 for (int k2 = 0; k2 < 2; ++k2) { u32x4 w;
; #pragma unroll
;                     for (int e = 0; e < 4; ++e) w[e] = cvt_pk_bf16(ph[8 * k2 + 2 * e], ph[8 * k2 + 2 * e + 1]);
;                     pf[k2] = __builtin_bit_cast(bf16x8, w); }
; #pragma unroll
;                 for (int db = 0; db < 2; ++db)
; #pragma unroll
;                     for (int k2 = 0; k2 < 2; ++k2) { const int ks = 2 * hf + k2; const v4i16_t lo = vtr(Vb + (16 * ks) * VPB + db * 64), hh = vtr(Vb + (16 * ks + 8) * VPB + db * 64);
;                         const bf16x8 vf = {lo[0], lo[1], lo[2], lo[3], hh[0], hh[1], hh[2], hh[3]};
;                         o[s][db] = MFMA32(vf, pf[k2], o[s][db]); }
.Lfd_641:
	v_exp_f32_e32 v80, v80
	v_exp_f32_e32 v81, v81
	v_exp_f32_e32 v140, v82
	v_exp_f32_e32 v141, v83
	v_exp_f32_e32 v84, v84
	v_exp_f32_e32 v85, v85
	v_exp_f32_e32 v86, v86
	v_exp_f32_e32 v87, v87
	v_exp_f32_e32 v88, v88
	v_exp_f32_e32 v89, v89
	v_exp_f32_e32 v90, v90
	v_exp_f32_e32 v91, v91
	v_pk_add_f32 v[82:83], v[80:81], v[140:141]
	v_exp_f32_e32 v92, v92
	v_exp_f32_e32 v93, v93
	v_pk_add_f32 v[82:83], v[84:85], v[82:83]
	v_exp_f32_e32 v94, v94
	v_exp_f32_e32 v95, v95
	v_pk_add_f32 v[82:83], v[86:87], v[82:83]
	v_cvt_pk_bf16_f32 v84, v84, v85
	v_pk_add_f32 v[82:83], v[88:89], v[82:83]
	v_cvt_pk_bf16_f32 v85, v86, v87
	v_pk_add_f32 v[82:83], v[90:91], v[82:83]
	v_cvt_pk_bf16_f32 v86, v88, v89
	v_pk_add_f32 v[82:83], v[92:93], v[82:83]
	v_cvt_pk_bf16_f32 v87, v90, v91
	v_pk_add_f32 v[142:143], v[94:95], v[82:83]
	v_cvt_pk_bf16_f32 v82, v80, v81
	v_cvt_pk_bf16_f32 v88, v92, v93
	v_cvt_pk_bf16_f32 v83, v140, v141
	v_cvt_pk_bf16_f32 v89, v94, v95
	v_add_f32_e32 v81, v142, v143
	s_waitcnt lgkmcnt(0)
	v_mfma_f32_32x32x16_bf16 v[0:15], v[204:207], v[82:85], v[0:15]
	v_add_f32_e32 v81, v126, v81
	v_max_f32_e32 v224, v64, v65
	v_mfma_f32_32x32x16_bf16 v[0:15], v[208:211], v[86:89], v[0:15]
	v_max3_f32 v224, v224, v66, v67
	v_max3_f32 v224, v224, v68, v69
	v_max3_f32 v224, v224, v70, v71
	v_max3_f32 v224, v224, v72, v73
	v_mfma_f32_32x32x16_bf16 v[16:31], v[212:215], v[82:85], v[16:31]
	v_max3_f32 v224, v224, v74, v75
	v_max3_f32 v224, v224, v76, v77
	v_max3_f32 v224, v224, v78, v79
	v_mfma_f32_32x32x16_bf16 v[16:31], v[216:219], v[86:89], v[16:31]
	v_cmp_lt_f32_e32 vcc, s61, v224
	s_cbranch_vccz .Lfd_643
	ds_bpermute_b32 v225, v184, v224
	s_waitcnt lgkmcnt(0)
	v_max_f32_e32 v225, v225, v225
	v_max_f32_e32 v224, v224, v225
	v_max_f32_e32 v222, v224, v224
	v_max_f32_e32 v223, 0, v222
	v_exp_f32_e64 v224, -v223
	v_add_f32_e32 v127, v127, v223
	v_xor_b32_e32 v222, 0x80000000, v127
	v_sub_f32_e32 v79, v79, v223
	v_sub_f32_e32 v78, v78, v223
	v_sub_f32_e32 v77, v77, v223
	v_sub_f32_e32 v76, v76, v223
	v_sub_f32_e32 v75, v75, v223
	v_sub_f32_e32 v74, v74, v223
	v_sub_f32_e32 v73, v73, v223
	v_sub_f32_e32 v72, v72, v223
	v_sub_f32_e32 v71, v71, v223
	v_sub_f32_e32 v70, v70, v223
	v_sub_f32_e32 v69, v69, v223
	v_sub_f32_e32 v68, v68, v223
	v_sub_f32_e32 v67, v67, v223
	v_sub_f32_e32 v66, v66, v223
	v_sub_f32_e32 v65, v65, v223
	v_sub_f32_e32 v64, v64, v223
	v_pk_mul_f32 v[14:15], v[14:15], v[224:225] op_sel_hi:[1,0]
	v_pk_mul_f32 v[12:13], v[12:13], v[224:225] op_sel_hi:[1,0]
	v_pk_mul_f32 v[10:11], v[10:11], v[224:225] op_sel_hi:[1,0]
	v_pk_mul_f32 v[8:9], v[8:9], v[224:225] op_sel_hi:[1,0]
	v_pk_mul_f32 v[6:7], v[6:7], v[224:225] op_sel_hi:[1,0]
	v_pk_mul_f32 v[4:5], v[4:5], v[224:225] op_sel_hi:[1,0]
	v_pk_mul_f32 v[2:3], v[2:3], v[224:225] op_sel_hi:[1,0]
	v_pk_mul_f32 v[0:1], v[0:1], v[224:225] op_sel_hi:[1,0]
	v_pk_mul_f32 v[30:31], v[30:31], v[224:225] op_sel_hi:[1,0]
	v_pk_mul_f32 v[28:29], v[28:29], v[224:225] op_sel_hi:[1,0]
	v_pk_mul_f32 v[26:27], v[26:27], v[224:225] op_sel_hi:[1,0]
	v_pk_mul_f32 v[24:25], v[24:25], v[224:225] op_sel_hi:[1,0]
	v_pk_mul_f32 v[22:23], v[22:23], v[224:225] op_sel_hi:[1,0]
	v_pk_mul_f32 v[20:21], v[20:21], v[224:225] op_sel_hi:[1,0]
	v_pk_mul_f32 v[18:19], v[18:19], v[224:225] op_sel_hi:[1,0]
	v_pk_mul_f32 v[16:17], v[16:17], v[224:225] op_sel_hi:[1,0]
	v_mul_f32_e32 v81, v81, v224
	v_mov_b32_e32 v48, v222
	v_mov_b32_e32 v49, v222
	v_mov_b32_e32 v50, v222
	v_mov_b32_e32 v51, v222
	v_mov_b32_e32 v52, v222
	v_mov_b32_e32 v53, v222
	v_mov_b32_e32 v54, v222
	v_mov_b32_e32 v55, v222
	v_mov_b32_e32 v56, v222
	v_mov_b32_e32 v57, v222
	v_mov_b32_e32 v58, v222
	v_mov_b32_e32 v59, v222
	v_mov_b32_e32 v60, v222
	v_mov_b32_e32 v61, v222
	v_mov_b32_e32 v62, v222
	v_mov_b32_e32 v63, v222
